# attnA far tiles: reference pre-subtracted via MFMA C operand (no per-element sub on the common path); sel far-tile K fragment reads batched
# speedup vs baseline: 1.0143x; 1.0113x over previous
; #define MFMA32(a, b, c) __builtin_amdgcn_mfma_f32_32x32x16_bf16((a), (b), (c), 0, 0, 0)
; DI float ex2(float x) { return __builtin_amdgcn_exp2f(x); }
; DI float xor32(float v) { return __shfl_xor(v, 32); }
; template <int NDT, int MODE, bool ALLON>
; DI void attn_tile(const bf16_t* Kl, int kst, const bf16_t* Vl, const bf16x8 (&q)[4], f32x16 (&O)[NDT], float& m, float& l,
;                   int kbase, int qp, int win, float cbias, const float* tab, bool lane_on) {
;     ...
;   for (int ks = 0; ks < 4; ++ks) {
;     const bf16x8 k0 = *(const bf16x8*)(Kl + lr * kst + ks * 16 + lh * 8);
;     const bf16x8 k1 = *(const bf16x8*)(Kl + (32 + lr) * kst + ks * 16 + lh * 8);
;     s[0] = MFMA32(k0, q[ks], s[0]);
;     s[1] = MFMA32(k1, q[ks], s[1]);
;   }
;   float alpha, psum = 0.f;
;   if (MODE == 0) {
;     float tmax = fmaxf(s[0][0], s[1][0]);
; #pragma unroll
;     for (int i = 1; i < 16; ++i) tmax = fmaxf(tmax, fmaxf(s[0][i], s[1][i]));
;     tmax = fmaxf(tmax, xor32(tmax)) + cbias;
;     if (!ALLON) tmax = lane_on ? tmax : -1e30f;
;     const float mn = fmaxf(m, tmax);
;     alpha = ex2(m - mn);
;     m = mn;
;     const float mc = (ALLON || lane_on) ? mn - cbias : 1e30f;
; #pragma unroll
;     for (int st = 0; st < 2; ++st)
; #pragma unroll
; DI void task_nsa(const P& p, int layer, int task, bf16_t* sm, int dm) {
;     ...
;       const bool on = (mymask >> j) & 1ull;
;       if (j * 64 <= qmin + 31 && __ballot(on)) {
;         if (j * 64 + 63 + 128 <= qmin)
;           attn_tile<2, 0, false>(Kl, 72, Vl, q, O, m, l, j * 64, qp, 0, tab[128], tab, on);
.LBB0_720:
	v_ffbl_b32_e32 v1, v1
	v_ffbl_b32_e32 v0, v0
	v_add_u32_e64 v1, v1, 32 clamp
	v_min_u32_e32 v0, v1, v0
	v_lshlrev_b32_e32 v32, 6, v0
	v_cmp_le_i32_e32 vcc, v32, v138
	s_waitcnt lgkmcnt(0)
	s_barrier
	s_and_saveexec_b64 s[8:9], vcc
	s_cbranch_execz .LBB0_797
	v_lshrrev_b64 v[0:1], v0, v[96:97]
	v_and_b32_e32 v0, 1, v0
	v_cmp_eq_u32_e64 s[4:5], 1, v0
	v_cmp_ne_u32_e32 vcc, 0, v0
	s_cbranch_vccz .LBB0_797
	v_cmp_le_i32_e32 vcc, v32, v137
	s_and_saveexec_b64 s[28:29], vcc
	s_xor_b64 s[28:29], exec, s[28:29]
	s_cbranch_execz .LBB0_727
	v_mov_b32_e32 v0, v195
	ds_read_b32 v144, v135 offset:37376
	s_nop 0
	v_and_b32_e32 v1, 31, v0
	v_lshrrev_b32_e32 v0, 2, v0
	v_mul_u32_u24_e32 v1, 0x48, v1
	v_and_b32_e32 v143, 8, v0
	v_lshlrev_b32_e32 v142, 1, v1
	v_lshlrev_b32_e32 v0, 1, v143
	v_add3_u32 v4, s45, v142, v0
	ds_read_b128 v[196:199], v4
	ds_read_b128 v[200:203], v4 offset:4608
	ds_read_b128 v[204:207], v4 offset:32
	ds_read_b128 v[208:211], v4 offset:4640
	ds_read_b128 v[212:215], v4 offset:64
	ds_read_b128 v[216:219], v4 offset:4672
	ds_read_b128 v[236:239], v4 offset:4704
	ds_read_b128 v[240:243], v4 offset:96
	s_waitcnt lgkmcnt(7)
	v_mfma_f32_32x32x16_bf16 v[48:63], v[196:199], v[64:67], 0
	s_waitcnt lgkmcnt(6)
	v_mfma_f32_32x32x16_bf16 v[32:47], v[200:203], v[64:67], 0
	s_waitcnt lgkmcnt(5)
	v_mfma_f32_32x32x16_bf16 v[48:63], v[204:207], v[68:71], v[48:63]
	s_waitcnt lgkmcnt(4)
	v_mfma_f32_32x32x16_bf16 v[32:47], v[208:211], v[68:71], v[32:47]
	s_waitcnt lgkmcnt(3)
	v_mfma_f32_32x32x16_bf16 v[48:63], v[212:215], v[72:75], v[48:63]
	s_waitcnt lgkmcnt(2)
	v_mfma_f32_32x32x16_bf16 v[32:47], v[216:219], v[72:75], v[32:47]
	s_waitcnt lgkmcnt(1)
	v_mfma_f32_32x32x16_bf16 v[32:47], v[236:239], v[76:79], v[32:47]
	s_waitcnt lgkmcnt(0)
	v_mfma_f32_32x32x16_bf16 v[48:63], v[240:243], v[76:79], v[48:63]
	s_nop 8
	v_max3_f32 v0, v32, v33, v34
	v_max3_f32 v0, v0, v35, v36
	v_max3_f32 v0, v0, v37, v38
	v_max3_f32 v0, v0, v39, v40
	v_max3_f32 v0, v0, v41, v42
	v_max3_f32 v0, v0, v43, v44
	v_max3_f32 v0, v0, v45, v46
	v_max_f32_e32 v0, v0, v47
	v_max3_f32 v1, v48, v49, v50
	v_max3_f32 v1, v1, v51, v52
	v_max3_f32 v1, v1, v53, v54
	v_max3_f32 v1, v1, v55, v56
	v_max3_f32 v1, v1, v57, v58
	v_max3_f32 v1, v1, v59, v60
	v_max3_f32 v1, v1, v61, v62
	v_max_f32_e32 v1, v1, v63
	v_max_f32_e32 v0, v0, v1
	ds_bpermute_b32 v1, v91, v0
	s_waitcnt lgkmcnt(0)
	v_max_f32_e32 v1, v1, v1
	v_max_f32_e32 v0, v0, v1
	v_add_f32_e32 v0, v144, v0
	v_cndmask_b32_e64 v0, v232, v0, s[4:5]
	v_add_f32_e32 v1, 0x41000000, v88
	v_cmp_gt_f32_e32 vcc, v0, v1
	s_nop 1
	v_cndmask_b32_e32 v141, v88, v0, vcc
	v_sub_f32_e32 v0, v88, v141
	v_exp_f32_e32 v88, v0
	s_nop 0
	v_cmp_neq_f32_e32 vcc, 1.0, v88
	s_cbranch_vccz .LBB0_799
	v_pk_mul_f32 v[160:161], v[160:161], v[88:89] op_sel_hi:[1,0]
	v_pk_mul_f32 v[162:163], v[162:163], v[88:89] op_sel_hi:[1,0]
	v_pk_mul_f32 v[164:165], v[164:165], v[88:89] op_sel_hi:[1,0]
	v_pk_mul_f32 v[166:167], v[166:167], v[88:89] op_sel_hi:[1,0]
	v_pk_mul_f32 v[168:169], v[168:169], v[88:89] op_sel_hi:[1,0]
	v_pk_mul_f32 v[170:171], v[170:171], v[88:89] op_sel_hi:[1,0]
	v_pk_mul_f32 v[172:173], v[172:173], v[88:89] op_sel_hi:[1,0]
	v_pk_mul_f32 v[174:175], v[174:175], v[88:89] op_sel_hi:[1,0]
	v_pk_mul_f32 v[176:177], v[176:177], v[88:89] op_sel_hi:[1,0]
	v_pk_mul_f32 v[178:179], v[178:179], v[88:89] op_sel_hi:[1,0]
	v_pk_mul_f32 v[180:181], v[180:181], v[88:89] op_sel_hi:[1,0]
	v_pk_mul_f32 v[182:183], v[182:183], v[88:89] op_sel_hi:[1,0]
	v_pk_mul_f32 v[184:185], v[184:185], v[88:89] op_sel_hi:[1,0]
	v_pk_mul_f32 v[186:187], v[186:187], v[88:89] op_sel_hi:[1,0]
	v_pk_mul_f32 v[188:189], v[188:189], v[88:89] op_sel_hi:[1,0]
	v_pk_mul_f32 v[190:191], v[190:191], v[88:89] op_sel_hi:[1,0]
	s_cbranch_execnz .LBB0_726

; DI int tidx() { int t = threadIdx.x; asm volatile("" : "+v"(t)); return t; }
; DI void task_attnA(const P& p, int layer, int task, bf16_t* sm, int dm) {
;   const int tid = tidx(), lane = tid & 63, wv = tid >> 6, c = wv & 1, qs = wv >> 1;
;   const int lr = lane & 31, lh = lane >> 5;
;   const int qb = 31 - (task >> 4), bh = task & 15, b = bh >> 2, h = bh & 3;
;   float* tab = (float*)((unsigned char*)sm + 71680);
;   bf16x8* qlds = (bf16x8*)((unsigned char*)sm + 72704) + wv * 256 + lane;
;   float* xbuf = (float*)((unsigned char*)sm);
;   __syncthreads();
;   if (tid < 129) tab[tid] = ((const float*)(p.ws + O_TABS))[h * 132 + tid];
;   const int q0 = qb * 128, qmin = q0 + qs * 32, qp = qmin + lr;
;   bf16_t* aq = (bf16_t*)(p.ws + O_AQ);
;   {
;     const bf16_t* qptr = aq + (size_t)(b * S_ + qp) * 512 + h * 128 + c * 64 + lh * 8;
; #pragma unroll
;     for (int ks = 0; ks < 4; ++ks) qlds[ks * 64] = *(const bf16x8*)(qptr + ks * 16);
;   }
;   f32x16 O[4];
; #pragma unroll
;   for (int dt = 0; dt < 4; ++dt)
; #pragma unroll
;     for (int i = 0; i < 16; ++i) O[dt][i] = 0.f;
;   float m = -1e30f, l = 0.f;
;   const bf16_t* kg = (const bf16_t*)(p.ws + O_AK) + (size_t)b * S_ * 512 + h * 128;
;   const bf16_t* vg = (const bf16_t*)(p.ws + O_AVT) + (size_t)((b * 4 + h) * 128) * S_;
;   u32x4 rk0, rk1, rv0, rv1;
;     ...
;   const int kt_hi = 2 * qb + 1;
;   A_GLOAD(0, 0) A_GLOAD(1, 0)
;   for (int kt = 0; kt <= kt_hi; ++kt) {
;     bf16_t* Kl = sm + (kt & 1) * 17920; const bf16_t* Vl = Kl + 64 * 136;
;     A_LSTORE(0) A_LSTORE(1)
;     if (kt < kt_hi) { A_GLOAD(0, kt + 1) A_GLOAD(1, kt + 1) }
;     __syncthreads();
.LBB0_974:
	s_or_b64 exec, exec, s[0:1]
	v_mov_b32_e32 v246, 0xf149f2ca
	v_lshlrev_b32_e32 v244, 2, v195
	v_add_u32_e32 v244, 0x1e000, v244
	s_waitcnt vmcnt(0)
	v_cmp_gt_u32_e64 s[98:99], s101, v247
	s_nop 1
	v_cndmask_b32_e64 v196, v246, v196, s[98:99]
	ds_write_b32 v244, v196
	s_add_i32 s3, s34, -16
	s_lshr_b32 s0, s3, 4
	s_xor_b32 s4, s0, 31
	v_ashrrev_i32_e32 v0, 2, v138
	s_lshl_b32 s5, s4, 7
	v_and_b32_e32 v27, 0xffffffe0, v0
	v_and_b32_e32 v139, 31, v138
	v_add_u32_e32 v28, s5, v27
	s_bfe_u32 s0, s34, 0x20002
	v_or_b32_e32 v0, v28, v139
	v_lshl_add_u32 v0, s0, 12, v0
	s_lshl_b32 s66, s2, 8
	s_lshl_b32 s0, s0, 22
	s_add_u32 s0, s56, s0
	v_ashrrev_i32_e32 v16, 4, v138
	s_addc_u32 s1, s57, 0
	v_ashrrev_i32_e32 v17, 31, v16
	s_add_u32 s0, s0, s66
	v_lshlrev_b64 v[18:19], 10, v[16:17]
	v_lshlrev_b32_e32 v17, 3, v138
	s_addc_u32 s1, s1, 0
	s_lshl_b32 s2, s3, 20
	v_and_b32_e32 v20, 0x78, v17
	s_and_b32 s2, s2, 0xf00000
	v_readlane_b32 s6, v253, 50
	v_lshlrev_b32_e32 v126, 1, v20
	v_ashrrev_i32_e32 v20, 3, v138
	v_readlane_b32 s7, v253, 51
	s_add_u32 s2, s6, s2
	v_ashrrev_i32_e32 v21, 31, v20
	v_ashrrev_i32_e32 v1, 31, v0
	s_addc_u32 s3, s7, 0
	v_lshlrev_b64 v[22:23], 13, v[20:21]
	v_and_b32_e32 v17, 56, v17
	v_ashrrev_i32_e32 v26, 6, v138
	v_lshlrev_b64 v[0:1], 10, v[0:1]
	v_lshl_add_u64 v[22:23], s[2:3], 0, v[22:23]
	v_lshlrev_b32_e32 v128, 1, v17
	v_mov_b32_e32 v129, v193
	v_add_u32_e32 v17, 0x200, v138
	v_and_b32_e32 v140, 1, v26
	v_lshl_add_u64 v[0:1], s[58:59], 0, v[0:1]
	v_lshl_add_u64 v[130:131], v[22:23], 0, v[128:129]
	v_ashrrev_i32_e32 v22, 4, v17
	v_bfe_u32 v137, v138, 5, 1
	v_lshl_add_u64 v[124:125], v[0:1], 0, s[66:67]
	v_lshlrev_b32_e32 v192, 7, v140
	v_ashrrev_i32_e32 v23, 31, v22
	v_lshl_add_u64 v[0:1], v[124:125], 0, v[192:193]
	v_lshlrev_b32_e32 v192, 4, v137
	v_lshl_add_u64 v[18:19], s[0:1], 0, v[18:19]
	v_mov_b32_e32 v127, v193
	v_lshlrev_b64 v[24:25], 10, v[22:23]
	v_lshl_add_u64 v[12:13], v[0:1], 0, v[192:193]
	v_lshl_add_u64 v[18:19], v[18:19], 0, v[126:127]
	v_lshl_add_u64 v[24:25], s[0:1], 0, v[24:25]
	global_load_dwordx4 v[0:3], v[12:13], off
	global_load_dwordx4 v[4:7], v[12:13], off offset:32
	global_load_dwordx4 v[8:11], v[12:13], off offset:64
	s_nop 0
	global_load_dwordx4 v[12:15], v[12:13], off offset:96
	v_lshl_add_u64 v[24:25], v[24:25], 0, v[126:127]
	global_load_dwordx4 v[96:99], v[18:19], off
	global_load_dwordx4 v[104:107], v[24:25], off
	v_ashrrev_i32_e32 v18, 3, v17
	v_ashrrev_i32_e32 v19, 31, v18
	v_lshlrev_b64 v[24:25], 13, v[18:19]
	v_lshl_add_u64 v[24:25], s[2:3], 0, v[24:25]
	v_lshl_add_u64 v[132:133], v[24:25], 0, v[128:129]
	global_load_dwordx4 v[100:103], v[130:131], off
	global_load_dwordx4 v[108:111], v[132:133], off
	v_and_b32_e32 v17, 63, v138
	v_lshlrev_b32_e32 v19, 12, v26
	v_lshlrev_b32_e32 v17, 4, v17
	v_readlane_b32 s3, v255, 5
	v_mov_b32_e32 v48, v193
	v_mov_b32_e32 v49, v193
	s_movk_i32 s2, 0x110
	v_add3_u32 v143, s3, v19, v17
	v_lshl_add_u64 v[134:135], s[0:1], 0, v[126:127]
	s_sub_i32 s0, s5, 59
	v_mov_b32_e32 v50, v193
	v_mul_lo_u32 v129, v16, s2
	v_mul_lo_u32 v141, v20, s89
	v_add_u32_e32 v142, 64, v16
	v_mul_lo_u32 v145, v22, s2
	v_mul_lo_u32 v146, v18, s89
	v_add_u32_e32 v147, 64, v22
	v_or_b32_e32 v148, 31, v28
	v_add_u32_e32 v149, 0xffffff41, v28
	s_lshl_b32 s6, s4, 1
	s_mov_b32 s66, 0
	v_add3_u32 v127, s0, v27, v139
	v_mov_b32_e32 v51, v193
	v_mov_b32_e32 v52, v193
	v_mov_b32_e32 v53, v193
	v_mov_b32_e32 v54, v193
	v_mov_b32_e32 v55, v193
	v_mov_b32_e32 v56, v193
	s_waitcnt vmcnt(7)
	ds_write_b128 v143, v[0:3]
	s_waitcnt vmcnt(6)
	ds_write_b128 v143, v[4:7] offset:1024
	s_waitcnt vmcnt(5)
	ds_write_b128 v143, v[8:11] offset:2048
	s_waitcnt vmcnt(4)
	ds_write_b128 v143, v[12:15] offset:3072
	v_mov_b32_e32 v57, v193
	v_mov_b32_e32 v58, v193
	v_mov_b32_e32 v59, v193
	v_mov_b32_e32 v60, v193
	v_mov_b32_e32 v61, v193
	v_mov_b32_e32 v62, v193
	v_mov_b32_e32 v63, v193
	v_mov_b64_e32 v[32:33], v[48:49]
	v_mov_b64_e32 v[16:17], v[48:49]
	v_mov_b64_e32 v[0:1], v[48:49]
	v_lshlrev_b32_e32 v144, 6, v140
	s_add_i32 s7, s6, 2
	v_mov_b32_e32 v154, 0xf149f2ca
	v_mov_b32_e32 v151, 0
	v_mov_b64_e32 v[34:35], v[50:51]
	v_mov_b64_e32 v[36:37], v[52:53]
	v_mov_b64_e32 v[38:39], v[54:55]
	v_mov_b64_e32 v[40:41], v[56:57]
	v_mov_b64_e32 v[42:43], v[58:59]
	v_mov_b64_e32 v[44:45], v[60:61]
	v_mov_b64_e32 v[46:47], v[62:63]
	v_mov_b64_e32 v[18:19], v[50:51]
	v_mov_b64_e32 v[20:21], v[52:53]
	v_mov_b64_e32 v[22:23], v[54:55]
	v_mov_b64_e32 v[24:25], v[56:57]
	v_mov_b64_e32 v[26:27], v[58:59]
	v_mov_b64_e32 v[28:29], v[60:61]
	v_mov_b64_e32 v[30:31], v[62:63]
	v_mov_b64_e32 v[2:3], v[50:51]
	v_mov_b64_e32 v[4:5], v[52:53]
	v_mov_b64_e32 v[6:7], v[54:55]
	v_mov_b64_e32 v[8:9], v[56:57]
	v_mov_b64_e32 v[10:11], v[58:59]
	v_mov_b64_e32 v[12:13], v[60:61]
	v_mov_b64_e32 v[14:15], v[62:63]
	s_mov_b32 s8, s66
	v_mov_b32_e32 v160, 0
	v_mov_b32_e32 v161, 0
	v_mov_b32_e32 v162, 0
	v_mov_b32_e32 v163, 0
	v_mov_b32_e32 v164, 0
	v_mov_b32_e32 v165, 0
	v_mov_b32_e32 v166, 0
	v_mov_b32_e32 v167, 0
	v_mov_b32_e32 v168, 0
	v_mov_b32_e32 v169, 0
	v_mov_b32_e32 v170, 0
	v_mov_b32_e32 v171, 0
	v_mov_b32_e32 v172, 0
	v_mov_b32_e32 v173, 0
	v_mov_b32_e32 v174, 0
	v_mov_b32_e32 v175, 0
	v_mov_b32_e32 v176, 0xf149f2ca
	v_mov_b32_e32 v177, 0
	s_branch .LBB0_978

; #define MFMA32(a, b, c) __builtin_amdgcn_mfma_f32_32x32x16_bf16((a), (b), (c), 0, 0, 0)
; DI float ex2(float x) { return __builtin_amdgcn_exp2f(x); }
; DI float xor32(float v) { return __shfl_xor(v, 32); }
; template <int NDT, int MODE, bool ALLON>
; DI void attn_tile(const bf16_t* Kl, int kst, const bf16_t* Vl, const bf16x8 (&q)[4], f32x16 (&O)[NDT], float& m, float& l,
;                   int kbase, int qp, int win, float cbias, const float* tab, bool lane_on) {
;     ...
;   for (int ks = 0; ks < 4; ++ks) {
;     const bf16x8 k0 = *(const bf16x8*)(Kl + lr * kst + ks * 16 + lh * 8);
;     const bf16x8 k1 = *(const bf16x8*)(Kl + (32 + lr) * kst + ks * 16 + lh * 8);
;     s[0] = MFMA32(k0, q[ks], s[0]);
;     s[1] = MFMA32(k1, q[ks], s[1]);
;   }
;   float alpha, psum = 0.f;
;   if (MODE == 0) {
;     float tmax = fmaxf(s[0][0], s[1][0]);
; #pragma unroll
;     for (int i = 1; i < 16; ++i) tmax = fmaxf(tmax, fmaxf(s[0][i], s[1][i]));
;     tmax = fmaxf(tmax, xor32(tmax)) + cbias;
;     if (!ALLON) tmax = lane_on ? tmax : -1e30f;
;     const float mn = fmaxf(m, tmax);
;     alpha = ex2(m - mn);
;     m = mn;
;     const float mc = (ALLON || lane_on) ? mn - cbias : 1e30f;
; #pragma unroll
;     for (int st = 0; st < 2; ++st)
; #pragma unroll
;       for (int i = 0; i < 16; ++i) { const float pe = ex2(s[st][i] - mc); psum += pe; s[st][i] = pe; }
; DI void task_attnA(const P& p, int layer, int task, bf16_t* sm, int dm) {
;     ...
;     if (kt * 64 <= qmin + 31) {
;       bf16x8 q[4];
; #pragma unroll
;       for (int ks = 0; ks < 4; ++ks) q[ks] = qlds[ks * 64];
;       if (kt * 64 + 63 + 128 <= qmin)
;         attn_tile<4, 0, true>(Kl + c * 64, 136, Vl, q, O, m, l, kt * 64, qp, 0, tab[128], tab, true);
.LBB0_980:
	v_cmp_le_i32_e32 vcc, s66, v148
	s_waitcnt lgkmcnt(0)
	s_barrier
	s_and_saveexec_b64 s[0:1], vcc
	s_cbranch_execz .LBB0_977
	ds_read_b128 v[64:67], v143
	ds_read_b128 v[120:123], v143 offset:1024
	ds_read_b128 v[116:119], v143 offset:2048
	ds_read_b128 v[112:115], v143 offset:3072
	v_cmp_le_i32_e32 vcc, s66, v149
	v_lshl_add_u32 v69, v144, 1, s9
	s_and_saveexec_b64 s[2:3], vcc
	s_xor_b64 s[2:3], exec, s[2:3]
	s_cbranch_execz .LBB0_985
	v_mov_b32_e32 v68, s81
	ds_read_b32 v155, v68
	v_cmp_neq_f32_e32 vcc, v154, v176
	s_cbranch_vccz .LattnA_cb_ok
	s_waitcnt lgkmcnt(0)
	v_sub_f32_e32 v177, v154, v155
	v_cmp_neq_f32_e32 vcc, v154, v232
	v_mov_b32_e32 v176, v154
	s_nop 1
	v_cndmask_b32_e32 v177, 0, v177, vcc
	v_sub_f32_e32 v160, 0, v177
	v_mov_b32_e32 v161, v160
	v_mov_b32_e32 v162, v160
	v_mov_b32_e32 v163, v160
	v_mov_b32_e32 v164, v160
	v_mov_b32_e32 v165, v160
	v_mov_b32_e32 v166, v160
	v_mov_b32_e32 v167, v160
	v_mov_b32_e32 v168, v160
	v_mov_b32_e32 v169, v160
	v_mov_b32_e32 v170, v160
	v_mov_b32_e32 v171, v160
	v_mov_b32_e32 v172, v160
	v_mov_b32_e32 v173, v160
	v_mov_b32_e32 v174, v160
	v_mov_b32_e32 v175, v160
.LattnA_cb_ok:
	v_mov_b32_e32 v68, v195
	s_nop 0
	v_and_b32_e32 v153, 31, v68
	v_lshrrev_b32_e32 v68, 2, v68
	v_and_b32_e32 v152, 8, v68
	v_mul_u32_u24_e32 v70, 0x110, v153
	v_lshlrev_b32_e32 v68, 1, v152
	v_add3_u32 v150, v69, v70, v68
	ds_read_b128 v[68:71], v150
	ds_read_b128 v[156:159], v150 offset:32
	s_waitcnt lgkmcnt(1)
	v_mfma_f32_32x32x16_bf16 v[80:95], v[68:71], v[64:67], v[160:175]
	ds_read_b128 v[68:71], v150 offset:8704
	s_waitcnt lgkmcnt(1)
	v_mfma_f32_32x32x16_bf16 v[80:95], v[156:159], v[120:123], v[80:95]
	ds_read_b128 v[156:159], v150 offset:8736
	s_waitcnt lgkmcnt(1)
	v_mfma_f32_32x32x16_bf16 v[64:79], v[68:71], v[64:67], v[160:175]
	s_waitcnt lgkmcnt(0)
	v_mfma_f32_32x32x16_bf16 v[64:79], v[156:159], v[120:123], v[64:79]
	ds_read_b128 v[120:123], v150 offset:64
	s_waitcnt lgkmcnt(0)
	v_mfma_f32_32x32x16_bf16 v[80:95], v[120:123], v[116:119], v[80:95]
	ds_read_b128 v[120:123], v150 offset:8768
	s_waitcnt lgkmcnt(0)
	v_mfma_f32_32x32x16_bf16 v[64:79], v[120:123], v[116:119], v[64:79]
	ds_read_b128 v[116:119], v150 offset:8800
	s_waitcnt lgkmcnt(0)
	v_mfma_f32_32x32x16_bf16 v[64:79], v[116:119], v[112:115], v[64:79]
	ds_read_b128 v[116:119], v150 offset:96
	s_waitcnt lgkmcnt(0)
	v_mfma_f32_32x32x16_bf16 v[80:95], v[116:119], v[112:115], v[80:95]
	s_nop 8
	v_max3_f32 v112, v64, v65, v66
	v_max3_f32 v112, v112, v67, v68
	v_max3_f32 v112, v112, v69, v70
	v_max3_f32 v112, v112, v71, v72
	v_max3_f32 v112, v112, v73, v74
	v_max3_f32 v112, v112, v75, v76
	v_max3_f32 v112, v112, v77, v78
	v_max_f32_e32 v112, v112, v79
	v_max3_f32 v113, v80, v81, v82
	v_max3_f32 v113, v113, v83, v84
	v_max3_f32 v113, v113, v85, v86
	v_max3_f32 v113, v113, v87, v88
	v_max3_f32 v113, v113, v89, v90
	v_max3_f32 v113, v113, v91, v92
	v_max3_f32 v113, v113, v93, v94
	v_max_f32_e32 v113, v113, v95
	v_max_f32_e32 v112, v112, v113
	v_and_b32_e32 v114, 64, v231
	v_xor_b32_e32 v113, 32, v231
	v_add_u32_e32 v114, 64, v114
	v_cmp_lt_i32_e32 vcc, v113, v114
	s_nop 1
	v_cndmask_b32_e32 v113, v231, v113, vcc
	v_lshlrev_b32_e32 v113, 2, v113
	ds_bpermute_b32 v113, v113, v112
	s_waitcnt lgkmcnt(0)
	v_max_f32_e32 v113, v113, v113
	v_max_f32_e32 v112, v112, v113
	v_cmp_lt_f32_e32 vcc, 0x41000000, v112
	v_cmp_eq_f32_e64 s[46:47], v154, v232
	s_nop 1
	s_or_b64 s[48:49], vcc, s[46:47]
	s_cbranch_scc0 .LattnA_fast
	v_add_f32_e32 v80, v177, v80
	v_add_f32_e32 v81, v177, v81
	v_add_f32_e32 v82, v177, v82
	v_add_f32_e32 v83, v177, v83
	v_add_f32_e32 v84, v177, v84
	v_add_f32_e32 v85, v177, v85
	v_add_f32_e32 v86, v177, v86
	v_add_f32_e32 v87, v177, v87
	v_add_f32_e32 v88, v177, v88
	v_add_f32_e32 v89, v177, v89
	v_add_f32_e32 v90, v177, v90
	v_add_f32_e32 v91, v177, v91
	v_add_f32_e32 v92, v177, v92
	v_add_f32_e32 v93, v177, v93
	v_add_f32_e32 v94, v177, v94
	v_add_f32_e32 v95, v177, v95
	v_add_f32_e32 v64, v177, v64
	v_add_f32_e32 v65, v177, v65
	v_add_f32_e32 v66, v177, v66
	v_add_f32_e32 v67, v177, v67
	v_add_f32_e32 v68, v177, v68
	v_add_f32_e32 v69, v177, v69
	v_add_f32_e32 v70, v177, v70
	v_add_f32_e32 v71, v177, v71
	v_add_f32_e32 v72, v177, v72
	v_add_f32_e32 v73, v177, v73
	v_add_f32_e32 v74, v177, v74
	v_add_f32_e32 v75, v177, v75
	v_add_f32_e32 v76, v177, v76
	v_add_f32_e32 v77, v177, v77
	v_add_f32_e32 v78, v177, v78
	v_add_f32_e32 v79, v177, v79
	v_add_f32_e32 v112, v177, v112
	v_add_f32_e32 v112, v155, v112
	v_add_f32_e32 v113, 0x41000000, v154
	v_cmp_gt_f32_e32 vcc, v112, v113
	s_nop 1
	v_cndmask_b32_e32 v150, v154, v112, vcc
	v_sub_f32_e32 v112, v154, v150
	v_exp_f32_e32 v112, v112
	s_nop 0
	v_cmp_neq_f32_e32 vcc, 1.0, v112
	s_cbranch_vccz .LBB0_984
	v_pk_mul_f32 v[62:63], v[62:63], v[112:113] op_sel_hi:[1,0]
	v_pk_mul_f32 v[60:61], v[60:61], v[112:113] op_sel_hi:[1,0]
	v_pk_mul_f32 v[58:59], v[58:59], v[112:113] op_sel_hi:[1,0]
	v_pk_mul_f32 v[56:57], v[56:57], v[112:113] op_sel_hi:[1,0]
	v_pk_mul_f32 v[54:55], v[54:55], v[112:113] op_sel_hi:[1,0]
	v_pk_mul_f32 v[52:53], v[52:53], v[112:113] op_sel_hi:[1,0]
	v_pk_mul_f32 v[50:51], v[50:51], v[112:113] op_sel_hi:[1,0]
	v_pk_mul_f32 v[48:49], v[48:49], v[112:113] op_sel_hi:[1,0]
	v_pk_mul_f32 v[46:47], v[46:47], v[112:113] op_sel_hi:[1,0]
	v_pk_mul_f32 v[44:45], v[44:45], v[112:113] op_sel_hi:[1,0]
	v_pk_mul_f32 v[42:43], v[42:43], v[112:113] op_sel_hi:[1,0]
	v_pk_mul_f32 v[40:41], v[40:41], v[112:113] op_sel_hi:[1,0]
	v_pk_mul_f32 v[38:39], v[38:39], v[112:113] op_sel_hi:[1,0]
	v_pk_mul_f32 v[36:37], v[36:37], v[112:113] op_sel_hi:[1,0]
	v_pk_mul_f32 v[34:35], v[34:35], v[112:113] op_sel_hi:[1,0]
	v_pk_mul_f32 v[32:33], v[32:33], v[112:113] op_sel_hi:[1,0]
	v_pk_mul_f32 v[30:31], v[30:31], v[112:113] op_sel_hi:[1,0]
	v_pk_mul_f32 v[28:29], v[28:29], v[112:113] op_sel_hi:[1,0]
	v_pk_mul_f32 v[26:27], v[26:27], v[112:113] op_sel_hi:[1,0]
	v_pk_mul_f32 v[24:25], v[24:25], v[112:113] op_sel_hi:[1,0]
	v_pk_mul_f32 v[22:23], v[22:23], v[112:113] op_sel_hi:[1,0]
	v_pk_mul_f32 v[20:21], v[20:21], v[112:113] op_sel_hi:[1,0]
	v_pk_mul_f32 v[18:19], v[18:19], v[112:113] op_sel_hi:[1,0]
	v_pk_mul_f32 v[16:17], v[16:17], v[112:113] op_sel_hi:[1,0]
	v_pk_mul_f32 v[14:15], v[14:15], v[112:113] op_sel_hi:[1,0]
	v_pk_mul_f32 v[12:13], v[12:13], v[112:113] op_sel_hi:[1,0]
	v_pk_mul_f32 v[10:11], v[10:11], v[112:113] op_sel_hi:[1,0]
	v_pk_mul_f32 v[8:9], v[8:9], v[112:113] op_sel_hi:[1,0]
	v_pk_mul_f32 v[6:7], v[6:7], v[112:113] op_sel_hi:[1,0]
	v_pk_mul_f32 v[4:5], v[4:5], v[112:113] op_sel_hi:[1,0]
	v_pk_mul_f32 v[2:3], v[2:3], v[112:113] op_sel_hi:[1,0]
	v_pk_mul_f32 v[0:1], v[0:1], v[112:113] op_sel_hi:[1,0]
; #define MFMA32(a, b, c) __builtin_amdgcn_mfma_f32_32x32x16_bf16((a), (b), (c), 0, 0, 0)
; DI unsigned pack2(float a, float b) { f32x2_t v = {a, b}; bf16x2_t r = __builtin_convertvector(v, bf16x2_t); return __builtin_bit_cast(unsigned, r); }
; DI float ex2(float x) { return __builtin_amdgcn_exp2f(x); }
; template <int NDT, int MODE, bool ALLON>
; DI void attn_tile(const bf16_t* Kl, int kst, const bf16_t* Vl, const bf16x8 (&q)[4], f32x16 (&O)[NDT], float& m, float& l,
;                   int kbase, int qp, int win, float cbias, const float* tab, bool lane_on) {
;     ...
;     const float mc = (ALLON || lane_on) ? mn - cbias : 1e30f;
; #pragma unroll
;     for (int st = 0; st < 2; ++st)
; #pragma unroll
;       for (int i = 0; i < 16; ++i) { const float pe = ex2(s[st][i] - mc); psum += pe; s[st][i] = pe; }
;     ...
;   l = l * alpha + psum;
;   if (__ballot(alpha != 1.f)) {
; #pragma unroll
;     for (int dt = 0; dt < NDT; ++dt)
; #pragma unroll
;       for (int i = 0; i < 16; ++i) O[dt][i] *= alpha;
;   }
; #pragma unroll
;   for (int st = 0; st < 2; ++st)
; #pragma unroll
;     for (int sk = 0; sk < 2; ++sk) {
;       u32x4 pu;
;       pu[0] = pack2(s[st][8 * sk + 0], s[st][8 * sk + 1]);
;       pu[1] = pack2(s[st][8 * sk + 2], s[st][8 * sk + 3]);
;       pu[2] = pack2(s[st][8 * sk + 4], s[st][8 * sk + 5]);
;       pu[3] = pack2(s[st][8 * sk + 6], s[st][8 * sk + 7]);
;       const bf16x8 pf = __builtin_bit_cast(bf16x8, pu);
; #pragma unroll
;       for (int dt = 0; dt < NDT; ++dt) {
;         const bf16_t* vp = Vl + (dt * 32 + lr) * 72 + st * 32 + sk * 16 + 4 * lh;
;         const uint2 v0 = *(const uint2*)(vp);
;         const uint2 v1 = *(const uint2*)(vp + 8);
;         u32x4 vu; vu[0] = v0.x; vu[1] = v0.y; vu[2] = v1.x; vu[3] = v1.y;
;         O[dt] = MFMA32(__builtin_bit_cast(bf16x8, vu), pf, O[dt]);
;       }
;     }
.LBB0_984:
	v_sub_f32_e32 v113, v150, v155
	v_sub_f32_e32 v80, v80, v113
	v_exp_f32_e32 v114, v80
	v_sub_f32_e32 v81, v81, v113
	v_exp_f32_e32 v115, v81
	v_sub_f32_e32 v81, v82, v113
	v_exp_f32_e32 v116, v81
	v_sub_f32_e32 v81, v83, v113
	v_exp_f32_e32 v117, v81
	v_sub_f32_e32 v81, v84, v113
	v_add_f32_e32 v80, 0, v114
	v_exp_f32_e32 v118, v81
	v_sub_f32_e32 v81, v85, v113
	v_add_f32_e32 v80, v115, v80
	v_exp_f32_e32 v119, v81
	v_sub_f32_e32 v81, v86, v113
	v_add_f32_e32 v80, v116, v80
	v_exp_f32_e32 v120, v81
	v_sub_f32_e32 v81, v87, v113
	v_add_f32_e32 v80, v117, v80
	v_exp_f32_e32 v121, v81
	v_sub_f32_e32 v81, v88, v113
	v_add_f32_e32 v80, v118, v80
	v_exp_f32_e32 v88, v81
	v_sub_f32_e32 v81, v89, v113
	v_add_f32_e32 v80, v119, v80
	v_exp_f32_e32 v89, v81
	v_sub_f32_e32 v81, v90, v113
	v_add_f32_e32 v80, v120, v80
	v_exp_f32_e32 v90, v81
	v_sub_f32_e32 v81, v91, v113
	v_add_f32_e32 v80, v121, v80
	v_exp_f32_e32 v91, v81
	v_sub_f32_e32 v81, v92, v113
	v_add_f32_e32 v80, v88, v80
	v_exp_f32_e32 v92, v81
	v_sub_f32_e32 v81, v93, v113
	v_add_f32_e32 v80, v89, v80
	v_exp_f32_e32 v93, v81
	v_sub_f32_e32 v81, v94, v113
	v_add_f32_e32 v80, v90, v80
	v_exp_f32_e32 v94, v81
	v_sub_f32_e32 v81, v95, v113
	v_add_f32_e32 v80, v91, v80
	v_exp_f32_e32 v95, v81
	v_add_f32_e32 v80, v92, v80
	v_add_f32_e32 v80, v93, v80
	v_add_f32_e32 v80, v94, v80
	v_sub_f32_e32 v64, v64, v113
	v_add_f32_e32 v81, v95, v80
	v_exp_f32_e32 v80, v64
	v_sub_f32_e32 v65, v65, v113
	v_cvt_pk_bf16_f32 v88, v88, v89
	v_cvt_pk_bf16_f32 v89, v90, v91
	v_add_f32_e32 v64, v80, v81
	v_exp_f32_e32 v81, v65
	v_sub_f32_e32 v65, v66, v113
	v_exp_f32_e32 v82, v65
	v_sub_f32_e32 v65, v67, v113
	v_exp_f32_e32 v83, v65
	v_sub_f32_e32 v65, v68, v113
	v_exp_f32_e32 v84, v65
	v_sub_f32_e32 v65, v69, v113
	v_add_f32_e32 v64, v81, v64
	v_exp_f32_e32 v85, v65
	v_sub_f32_e32 v65, v70, v113
	v_add_f32_e32 v64, v82, v64
	v_exp_f32_e32 v86, v65
	v_sub_f32_e32 v65, v71, v113
	v_add_f32_e32 v64, v83, v64
	v_exp_f32_e32 v87, v65
	v_add_f32_e32 v64, v84, v64
	v_add_f32_e32 v64, v85, v64
	v_add_f32_e32 v64, v86, v64
	v_add_f32_e32 v65, v87, v64
	v_sub_f32_e32 v64, v72, v113
	v_exp_f32_e32 v64, v64
	v_sub_f32_e32 v69, v76, v113
	v_exp_f32_e32 v69, v69
	v_sub_f32_e32 v70, v77, v113
	v_add_f32_e32 v66, v64, v65
	v_sub_f32_e32 v65, v73, v113
	v_exp_f32_e32 v65, v65
	v_exp_f32_e32 v70, v70
	v_sub_f32_e32 v71, v78, v113
	v_exp_f32_e32 v71, v71
	v_add_f32_e32 v67, v65, v66
	v_sub_f32_e32 v66, v74, v113
	v_exp_f32_e32 v66, v66
	v_sub_f32_e32 v72, v79, v113
	v_exp_f32_e32 v72, v72
	v_mul_u32_u24_e32 v73, 0x48, v153
	v_add_f32_e32 v68, v66, v67
	v_sub_f32_e32 v67, v75, v113
	v_exp_f32_e32 v67, v67
	v_lshlrev_b32_e32 v73, 1, v73
	v_add3_u32 v73, s9, v152, v73
	v_add_u32_e32 v74, 0x4000, v73
	v_add_f32_e32 v68, v67, v68
	v_add_f32_e32 v68, v69, v68
	v_add_f32_e32 v68, v70, v68
	v_add_f32_e32 v68, v71, v68
	v_add_f32_e32 v68, v72, v68
	v_fmac_f32_e32 v68, v151, v112
	v_cvt_pk_bf16_f32 v112, v114, v115
	v_cvt_pk_bf16_f32 v113, v116, v117
	v_cvt_pk_bf16_f32 v114, v118, v119
	ds_read2_b64 v[76:79], v74 offset0:128 offset1:130
	ds_read2_b64 v[116:119], v74 offset0:132 offset1:134
	v_cvt_pk_bf16_f32 v115, v120, v121
	v_cvt_pk_bf16_f32 v90, v92, v93
	v_cvt_pk_bf16_f32 v91, v94, v95
	s_waitcnt lgkmcnt(1)
	v_mfma_f32_32x32x16_bf16 v[48:63], v[76:79], v[112:115], v[48:63]
	v_add_u32_e32 v76, 0x5000, v73
	ds_read2_b64 v[120:123], v76 offset0:192 offset1:194
	v_cvt_pk_bf16_f32 v78, v80, v81
	v_cvt_pk_bf16_f32 v79, v82, v83
	v_cvt_pk_bf16_f32 v80, v84, v85
	ds_read2_b64 v[82:85], v74 offset0:136 offset1:138
	v_add_u32_e32 v75, 0x6800, v73
	s_waitcnt lgkmcnt(2)
	v_mfma_f32_32x32x16_bf16 v[48:63], v[116:119], v[88:91], v[48:63]
	ds_read2_b64 v[92:95], v76 offset0:196 offset1:198
	v_cvt_pk_bf16_f32 v81, v86, v87
	v_add_u32_e32 v73, 0x7800, v73
	v_cvt_pk_bf16_f32 v64, v64, v65
	v_cvt_pk_bf16_f32 v65, v66, v67
	v_cvt_pk_bf16_f32 v66, v69, v70
	v_cvt_pk_bf16_f32 v67, v71, v72
	s_waitcnt lgkmcnt(2)
	v_mfma_f32_32x32x16_bf16 v[32:47], v[120:123], v[112:115], v[32:47]
	ds_read2_b64 v[120:123], v75 offset1:2
	s_waitcnt lgkmcnt(2)
	v_mfma_f32_32x32x16_bf16 v[48:63], v[82:85], v[78:81], v[48:63]
	ds_read2_b64 v[82:85], v76 offset0:200 offset1:202
	s_waitcnt lgkmcnt(2)
	v_mfma_f32_32x32x16_bf16 v[32:47], v[92:95], v[88:91], v[32:47]
	ds_read2_b64 v[92:95], v75 offset0:4 offset1:6
	s_waitcnt lgkmcnt(2)
	v_mfma_f32_32x32x16_bf16 v[16:31], v[120:123], v[112:115], v[16:31]
	ds_read2_b64 v[120:123], v73 offset0:64 offset1:66
	s_waitcnt lgkmcnt(2)
	v_mfma_f32_32x32x16_bf16 v[32:47], v[82:85], v[78:81], v[32:47]
	ds_read2_b64 v[82:85], v75 offset0:8 offset1:10
	s_waitcnt lgkmcnt(2)
	v_mfma_f32_32x32x16_bf16 v[16:31], v[92:95], v[88:91], v[16:31]
	ds_read2_b64 v[92:95], v73 offset0:68 offset1:70
	s_waitcnt lgkmcnt(2)
	v_mfma_f32_32x32x16_bf16 v[0:15], v[120:123], v[112:115], v[0:15]
	s_waitcnt lgkmcnt(1)
	v_mfma_f32_32x32x16_bf16 v[16:31], v[82:85], v[78:81], v[16:31]
	ds_read2_b64 v[82:85], v73 offset0:72 offset1:74
	ds_read2_b64 v[70:73], v73 offset0:76 offset1:78
	s_waitcnt lgkmcnt(2)
	v_mfma_f32_32x32x16_bf16 v[0:15], v[92:95], v[88:91], v[0:15]
	s_waitcnt lgkmcnt(1)
	v_mfma_f32_32x32x16_bf16 v[0:15], v[82:85], v[78:81], v[0:15]
	ds_read2_b64 v[78:81], v74 offset0:140 offset1:142
	s_waitcnt lgkmcnt(0)
	v_mfma_f32_32x32x16_bf16 v[48:63], v[78:81], v[64:67], v[48:63]
	ds_read2_b64 v[76:79], v76 offset0:204 offset1:206
	s_waitcnt lgkmcnt(0)
	v_mfma_f32_32x32x16_bf16 v[32:47], v[76:79], v[64:67], v[32:47]
	ds_read2_b64 v[74:77], v75 offset0:12 offset1:14
	s_waitcnt lgkmcnt(0)
	v_mfma_f32_32x32x16_bf16 v[16:31], v[74:77], v[64:67], v[16:31]
	v_mfma_f32_32x32x16_bf16 v[0:15], v[70:73], v[64:67], v[0:15]
	s_branch .LBB0_985
; #define MFMA32(a, b, c) __builtin_amdgcn_mfma_f32_32x32x16_bf16((a), (b), (c), 0, 0, 0)
; DI unsigned pack2(float a, float b) { f32x2_t v = {a, b}; bf16x2_t r = __builtin_convertvector(v, bf16x2_t); return __builtin_bit_cast(unsigned, r); }
; DI float ex2(float x) { return __builtin_amdgcn_exp2f(x); }
; template <int NDT, int MODE, bool ALLON>
; DI void attn_tile(const bf16_t* Kl, int kst, const bf16_t* Vl, const bf16x8 (&q)[4], f32x16 (&O)[NDT], float& m, float& l,
;                   int kbase, int qp, int win, float cbias, const float* tab, bool lane_on) {
;     ...
;     const float mc = (ALLON || lane_on) ? mn - cbias : 1e30f;
; #pragma unroll
;     for (int st = 0; st < 2; ++st)
; #pragma unroll
;       for (int i = 0; i < 16; ++i) { const float pe = ex2(s[st][i] - mc); psum += pe; s[st][i] = pe; }
;     ...
;   l = l * alpha + psum;
;   if (__ballot(alpha != 1.f)) {
; #pragma unroll
;     for (int dt = 0; dt < NDT; ++dt)
; #pragma unroll
;       for (int i = 0; i < 16; ++i) O[dt][i] *= alpha;
;   }
; #pragma unroll
;   for (int st = 0; st < 2; ++st)
; #pragma unroll
;     for (int sk = 0; sk < 2; ++sk) {
;       u32x4 pu;
;       pu[0] = pack2(s[st][8 * sk + 0], s[st][8 * sk + 1]);
;       pu[1] = pack2(s[st][8 * sk + 2], s[st][8 * sk + 3]);
;       pu[2] = pack2(s[st][8 * sk + 4], s[st][8 * sk + 5]);
;       pu[3] = pack2(s[st][8 * sk + 6], s[st][8 * sk + 7]);
;       const bf16x8 pf = __builtin_bit_cast(bf16x8, pu);
; #pragma unroll
;       for (int dt = 0; dt < NDT; ++dt) {
;         const bf16_t* vp = Vl + (dt * 32 + lr) * 72 + st * 32 + sk * 16 + 4 * lh;
;         const uint2 v0 = *(const uint2*)(vp);
;         const uint2 v1 = *(const uint2*)(vp + 8);
;         u32x4 vu; vu[0] = v0.x; vu[1] = v0.y; vu[2] = v1.x; vu[3] = v1.y;
;         O[dt] = MFMA32(__builtin_bit_cast(bf16x8, vu), pf, O[dt]);
;       }
;     }
.LattnA_fast:
	v_mov_b32_e32 v150, v154
	v_exp_f32_e32 v114, v80
	v_exp_f32_e32 v115, v81
	v_exp_f32_e32 v116, v82
	v_exp_f32_e32 v117, v83
	v_add_f32_e32 v80, 0, v114
	v_exp_f32_e32 v118, v84
	v_add_f32_e32 v80, v115, v80
	v_exp_f32_e32 v119, v85
	v_add_f32_e32 v80, v116, v80
	v_exp_f32_e32 v120, v86
	v_add_f32_e32 v80, v117, v80
	v_exp_f32_e32 v121, v87
	v_add_f32_e32 v80, v118, v80
	v_exp_f32_e32 v88, v88
	v_add_f32_e32 v80, v119, v80
	v_exp_f32_e32 v89, v89
	v_add_f32_e32 v80, v120, v80
	v_exp_f32_e32 v90, v90
	v_add_f32_e32 v80, v121, v80
	v_exp_f32_e32 v91, v91
	v_add_f32_e32 v80, v88, v80
	v_exp_f32_e32 v92, v92
	v_add_f32_e32 v80, v89, v80
	v_exp_f32_e32 v93, v93
	v_add_f32_e32 v80, v90, v80
	v_exp_f32_e32 v94, v94
	v_add_f32_e32 v80, v91, v80
	v_exp_f32_e32 v95, v95
	v_add_f32_e32 v80, v92, v80
	v_add_f32_e32 v80, v93, v80
	v_add_f32_e32 v80, v94, v80
	v_add_f32_e32 v81, v95, v80
	v_exp_f32_e32 v80, v64
	v_cvt_pk_bf16_f32 v88, v88, v89
	v_cvt_pk_bf16_f32 v89, v90, v91
	v_add_f32_e32 v64, v80, v81
	v_exp_f32_e32 v81, v65
	v_exp_f32_e32 v82, v66
	v_exp_f32_e32 v83, v67
	v_exp_f32_e32 v84, v68
	v_add_f32_e32 v64, v81, v64
	v_exp_f32_e32 v85, v69
	v_add_f32_e32 v64, v82, v64
	v_exp_f32_e32 v86, v70
	v_add_f32_e32 v64, v83, v64
	v_exp_f32_e32 v87, v71
	v_add_f32_e32 v64, v84, v64
	v_add_f32_e32 v64, v85, v64
	v_add_f32_e32 v64, v86, v64
	v_add_f32_e32 v65, v87, v64
	v_exp_f32_e32 v64, v72
	v_exp_f32_e32 v69, v76
	v_add_f32_e32 v66, v64, v65
	v_exp_f32_e32 v65, v73
	v_exp_f32_e32 v70, v77
	v_exp_f32_e32 v71, v78
	v_add_f32_e32 v67, v65, v66
	v_exp_f32_e32 v66, v74
	v_exp_f32_e32 v72, v79
	v_mul_u32_u24_e32 v73, 0x48, v153
	v_add_f32_e32 v68, v66, v67
	v_exp_f32_e32 v67, v75
	v_lshlrev_b32_e32 v73, 1, v73
	v_add3_u32 v73, s9, v152, v73
	v_add_u32_e32 v74, 0x4000, v73
	v_add_f32_e32 v68, v67, v68
	v_add_f32_e32 v68, v69, v68
	v_add_f32_e32 v68, v70, v68
	v_add_f32_e32 v68, v71, v68
	v_add_f32_e32 v68, v72, v68
	v_add_f32_e32 v68, v68, v151
	v_cvt_pk_bf16_f32 v112, v114, v115
	v_cvt_pk_bf16_f32 v113, v116, v117
	v_cvt_pk_bf16_f32 v114, v118, v119
	ds_read2_b64 v[76:79], v74 offset0:128 offset1:130
	ds_read2_b64 v[116:119], v74 offset0:132 offset1:134
	v_cvt_pk_bf16_f32 v115, v120, v121
	v_cvt_pk_bf16_f32 v90, v92, v93
	v_cvt_pk_bf16_f32 v91, v94, v95
	s_waitcnt lgkmcnt(1)
	v_mfma_f32_32x32x16_bf16 v[48:63], v[76:79], v[112:115], v[48:63]
	v_add_u32_e32 v76, 0x5000, v73
	ds_read2_b64 v[120:123], v76 offset0:192 offset1:194
	v_cvt_pk_bf16_f32 v78, v80, v81
	v_cvt_pk_bf16_f32 v79, v82, v83
	v_cvt_pk_bf16_f32 v80, v84, v85
	ds_read2_b64 v[82:85], v74 offset0:136 offset1:138
	v_add_u32_e32 v75, 0x6800, v73
	s_waitcnt lgkmcnt(2)
	v_mfma_f32_32x32x16_bf16 v[48:63], v[116:119], v[88:91], v[48:63]
	ds_read2_b64 v[92:95], v76 offset0:196 offset1:198
	v_cvt_pk_bf16_f32 v81, v86, v87
	v_add_u32_e32 v73, 0x7800, v73
	v_cvt_pk_bf16_f32 v64, v64, v65
	v_cvt_pk_bf16_f32 v65, v66, v67
	v_cvt_pk_bf16_f32 v66, v69, v70
	v_cvt_pk_bf16_f32 v67, v71, v72
	s_waitcnt lgkmcnt(2)
	v_mfma_f32_32x32x16_bf16 v[32:47], v[120:123], v[112:115], v[32:47]
	ds_read2_b64 v[120:123], v75 offset1:2
	s_waitcnt lgkmcnt(2)
	v_mfma_f32_32x32x16_bf16 v[48:63], v[82:85], v[78:81], v[48:63]
	ds_read2_b64 v[82:85], v76 offset0:200 offset1:202
	s_waitcnt lgkmcnt(2)
	v_mfma_f32_32x32x16_bf16 v[32:47], v[92:95], v[88:91], v[32:47]
	ds_read2_b64 v[92:95], v75 offset0:4 offset1:6
	s_waitcnt lgkmcnt(2)
	v_mfma_f32_32x32x16_bf16 v[16:31], v[120:123], v[112:115], v[16:31]
	ds_read2_b64 v[120:123], v73 offset0:64 offset1:66
	s_waitcnt lgkmcnt(2)
	v_mfma_f32_32x32x16_bf16 v[32:47], v[82:85], v[78:81], v[32:47]
	ds_read2_b64 v[82:85], v75 offset0:8 offset1:10
	s_waitcnt lgkmcnt(2)
	v_mfma_f32_32x32x16_bf16 v[16:31], v[92:95], v[88:91], v[16:31]
	ds_read2_b64 v[92:95], v73 offset0:68 offset1:70
	s_waitcnt lgkmcnt(2)
	v_mfma_f32_32x32x16_bf16 v[0:15], v[120:123], v[112:115], v[0:15]
	s_waitcnt lgkmcnt(1)
	v_mfma_f32_32x32x16_bf16 v[16:31], v[82:85], v[78:81], v[16:31]
	ds_read2_b64 v[82:85], v73 offset0:72 offset1:74
	ds_read2_b64 v[70:73], v73 offset0:76 offset1:78
	s_waitcnt lgkmcnt(2)
	v_mfma_f32_32x32x16_bf16 v[0:15], v[92:95], v[88:91], v[0:15]
	s_waitcnt lgkmcnt(1)
	v_mfma_f32_32x32x16_bf16 v[0:15], v[82:85], v[78:81], v[0:15]
	ds_read2_b64 v[78:81], v74 offset0:140 offset1:142
	s_waitcnt lgkmcnt(0)
	v_mfma_f32_32x32x16_bf16 v[48:63], v[78:81], v[64:67], v[48:63]
	ds_read2_b64 v[76:79], v76 offset0:204 offset1:206
	s_waitcnt lgkmcnt(0)
	v_mfma_f32_32x32x16_bf16 v[32:47], v[76:79], v[64:67], v[32:47]
	ds_read2_b64 v[74:77], v75 offset0:12 offset1:14
	s_waitcnt lgkmcnt(0)
	v_mfma_f32_32x32x16_bf16 v[16:31], v[74:77], v[64:67], v[16:31]
	v_mfma_f32_32x32x16_bf16 v[0:15], v[70:73], v[64:67], v[0:15]
